# v55: v53 + QK variant dispatch without the second flag test, static-path s_nop 6 dropped, loop-carried scalar moves ahead of the tile barrier
# baseline (speedup 1.0000x reference)
; DI f32x16 mfma32(bf16x8 a, bf16x8 b, f32x16 c) { return __builtin_amdgcn_mfma_f32_32x32x16_bf16(a, b, c, 0, 0, 0); }
; template <int PM> DI void attn_phase(const Params& p, int l, char* smem, int* s_item, int wv, int cidx) {
;     ...
;         if (active) {
; #pragma unroll
;           for (int kb = 0; kb < 2; ++kb)
; #pragma unroll
;             for (int e = 0; e < 16; ++e) sacc[kb][e] = 0.f;
;           const char* Kc = Kb0 + cur * 17408 + l31 * 272 + dofs_b + h * 16;
;           bf16x8 kf[8];
;           if (full_d) {
; #pragma unroll
;             for (int j = 0; j < 8; ++j) kf[j] = *(const bf16x8*)(Kc + (j >> 3) * 32 * 272 + (j & 7) * 32);
; #pragma unroll
;             for (int j = 0; j < 16; ++j) {
;               sacc[j >> 3] = mfma32(kf[j & 7], qf[j & 7], sacc[j >> 3]);
;               if (j + 8 < 16) kf[j & 7] = *(const bf16x8*)(Kc + ((j + 8) >> 3) * 32 * 272 + ((j + 8) & 7) * 32);
;               __builtin_amdgcn_sched_barrier(0);
;             }
;           } else {
; #pragma unroll
;             for (int j = 0; j < 4; ++j) kf[j] = *(const bf16x8*)(Kc + (j >> 2) * 32 * 272 + (j & 3) * 32);
; #pragma unroll
;             for (int j = 0; j < 8; ++j) {
;               sacc[j >> 2] = mfma32(kf[j & 3], qf[j & 3], sacc[j >> 2]);
;               if (j + 4 < 8) kf[j & 3] = *(const bf16x8*)(Kc + ((j + 4) >> 2) * 32 * 272 + ((j + 4) & 3) * 32);
;               __builtin_amdgcn_sched_barrier(0);
;             }
;           }
.LBB0_435:
	s_andn2_b64 s[74:75], exec, s[2:3]
	s_andn2_b64 vcc, exec, s[2:3]
	s_mulk_i32 s95, 0x5000
	s_cbranch_vccnz .LBB0_441
	s_mulk_i32 s89, 0x4400
	v_add_u32_e32 v0, s89, v234
	ds_read_b128 v[48:51], v0
	ds_read_b128 v[10:13], v0 offset:32
	ds_read_b128 v[6:9], v0 offset:64
	ds_read_b128 v[2:5], v0 offset:96
	s_and_b64 vcc, exec, s[72:73]
	s_cbranch_vccnz .Lqk_half
	ds_read_b128 v[32:35], v0 offset:128
	ds_read_b128 v[36:39], v0 offset:160
	ds_read_b128 v[40:43], v0 offset:192
	ds_read_b128 v[44:47], v0 offset:224
	ds_read_b128 v[52:55], v0 offset:8704
	s_waitcnt lgkmcnt(8)
	v_mfma_f32_32x32x16_bf16 v[16:31], v[48:51], v[148:151], 0
	s_waitcnt lgkmcnt(7)
	v_mfma_f32_32x32x16_bf16 v[16:31], v[10:13], v[152:155], v[16:31]
	ds_read_b128 v[56:59], v0 offset:8736
	s_waitcnt lgkmcnt(7)
	v_mfma_f32_32x32x16_bf16 v[16:31], v[6:9], v[156:159], v[16:31]
	ds_read_b128 v[60:63], v0 offset:8768
	s_waitcnt lgkmcnt(7)
	v_mfma_f32_32x32x16_bf16 v[16:31], v[2:5], v[160:163], v[16:31]
	ds_read_b128 v[64:67], v0 offset:8800
	s_waitcnt lgkmcnt(7)
	v_mfma_f32_32x32x16_bf16 v[16:31], v[32:35], v[164:167], v[16:31]
	ds_read_b128 v[68:71], v0 offset:8832
	s_waitcnt lgkmcnt(7)
	v_mfma_f32_32x32x16_bf16 v[16:31], v[36:39], v[168:171], v[16:31]
	ds_read_b128 v[72:75], v0 offset:8864
	s_waitcnt lgkmcnt(7)
	v_mfma_f32_32x32x16_bf16 v[16:31], v[40:43], v[172:175], v[16:31]
	ds_read_b128 v[76:79], v0 offset:8896
	s_waitcnt lgkmcnt(7)
	v_mfma_f32_32x32x16_bf16 v[16:31], v[44:47], v[176:179], v[16:31]
	ds_read_b128 v[144:147], v0 offset:8928
	s_waitcnt lgkmcnt(7)
	v_mfma_f32_32x32x16_bf16 v[32:47], v[52:55], v[148:151], 0
	s_waitcnt lgkmcnt(6)
	v_mfma_f32_32x32x16_bf16 v[32:47], v[56:59], v[152:155], v[32:47]
	s_waitcnt lgkmcnt(5)
	v_mfma_f32_32x32x16_bf16 v[32:47], v[60:63], v[156:159], v[32:47]
	s_waitcnt lgkmcnt(4)
	v_mfma_f32_32x32x16_bf16 v[32:47], v[64:67], v[160:163], v[32:47]
	s_waitcnt lgkmcnt(3)
	v_mfma_f32_32x32x16_bf16 v[32:47], v[68:71], v[164:167], v[32:47]
	s_waitcnt lgkmcnt(2)
	v_mfma_f32_32x32x16_bf16 v[32:47], v[72:75], v[168:171], v[32:47]
	s_waitcnt lgkmcnt(1)
	v_mfma_f32_32x32x16_bf16 v[32:47], v[76:79], v[172:175], v[32:47]
	s_waitcnt lgkmcnt(0)
	v_mfma_f32_32x32x16_bf16 v[32:47], v[144:147], v[176:179], v[32:47]
	s_branch .LBB0_440
.Lqk_half:
	s_waitcnt lgkmcnt(3)
	v_mfma_f32_32x32x16_bf16 v[16:31], v[48:51], v[148:151], 0
	ds_read_b128 v[32:35], v0 offset:8704
	s_waitcnt lgkmcnt(3)
	v_mfma_f32_32x32x16_bf16 v[16:31], v[10:13], v[152:155], v[16:31]
	ds_read_b128 v[10:13], v0 offset:8736
	s_waitcnt lgkmcnt(3)
	v_mfma_f32_32x32x16_bf16 v[16:31], v[6:9], v[156:159], v[16:31]
	ds_read_b128 v[6:9], v0 offset:8768
	s_waitcnt lgkmcnt(3)
	v_mfma_f32_32x32x16_bf16 v[16:31], v[2:5], v[160:163], v[16:31]
	ds_read_b128 v[2:5], v0 offset:8800
	s_waitcnt lgkmcnt(3)
	v_mfma_f32_32x32x16_bf16 v[32:47], v[32:35], v[148:151], 0
	s_waitcnt lgkmcnt(2)
	v_mfma_f32_32x32x16_bf16 v[32:47], v[10:13], v[152:155], v[32:47]
	s_waitcnt lgkmcnt(1)
	v_mfma_f32_32x32x16_bf16 v[32:47], v[6:9], v[156:159], v[32:47]
	s_waitcnt lgkmcnt(0)
	v_mfma_f32_32x32x16_bf16 v[32:47], v[2:5], v[160:163], v[32:47]

; template <int PM> DI void attn_phase(const Params& p, int l, char* smem, int* s_item, int wv, int cidx) {
;     ...
;         vcur = vnext;
;         __syncthreads();
.LBB0_515:
	s_add_i32 s92, s92, 64
	s_cmp_eq_u32 s81, s94
	s_mov_b32 s95, s93
	s_mov_b32 s2, s94
	s_waitcnt lgkmcnt(0)
	s_barrier
	s_cbranch_scc1 .LBB0_518
	s_branch .LBB0_422
